# polling loops (grid barrier spins, team-order waits, flag polls) sleep 4x shorter between polls
# baseline (speedup 1.0000x reference)
.LBB0_47:
	global_load_dword v140, v131, s[70:71] offset:2048 sc1
	s_mov_b64 s[2:3], -1
	s_waitcnt vmcnt(0)
	v_readfirstlane_b32 s4, v140
	s_cmpk_gt_u32 s4, 0xbf
	s_mov_b64 s[4:5], -1
	s_cbranch_scc1 .LBB0_46
	s_sleep 4
	global_load_dword v140, v131, s[70:71] offset:2048 sc1
	s_waitcnt vmcnt(0)
	v_readfirstlane_b32 s4, v140
	s_cmpk_lt_u32 s4, 0xc0
	s_mov_b64 s[4:5], -1
	s_cbranch_scc0 .LBB0_46
	s_sleep 4
	global_load_dword v140, v131, s[70:71] offset:2048 sc1
	s_waitcnt vmcnt(0)
	v_readfirstlane_b32 s4, v140
	s_cmpk_lt_u32 s4, 0xc0
	s_mov_b64 s[4:5], -1
	s_cbranch_scc0 .LBB0_46
	s_sleep 4
	global_load_dword v140, v131, s[70:71] offset:2048 sc1
	s_waitcnt vmcnt(0)
	v_readfirstlane_b32 s4, v140
	s_cmpk_lt_u32 s4, 0xc0
	s_mov_b64 s[4:5], -1
	s_cbranch_scc0 .LBB0_46
	s_sleep 4
	global_load_dword v140, v131, s[70:71] offset:2048 sc1
	s_waitcnt vmcnt(0)
	v_readfirstlane_b32 s4, v140
	s_cmpk_lt_u32 s4, 0xc0
	s_mov_b64 s[4:5], -1
	s_cbranch_scc0 .LBB0_46
	s_sleep 4
	global_load_dword v140, v131, s[70:71] offset:2048 sc1
	s_waitcnt vmcnt(0)
	v_readfirstlane_b32 s4, v140
	s_cmpk_lt_u32 s4, 0xc0
	s_mov_b64 s[4:5], -1
	s_cbranch_scc0 .LBB0_46
	s_sleep 4
	global_load_dword v140, v131, s[70:71] offset:2048 sc1
	s_waitcnt vmcnt(0)
	v_readfirstlane_b32 s4, v140
	s_cmpk_lt_u32 s4, 0xc0
	s_mov_b64 s[4:5], -1
	s_cbranch_scc0 .LBB0_46
	s_sleep 4
	global_load_dword v140, v131, s[70:71] offset:2048 sc1
	s_waitcnt vmcnt(0)
	v_readfirstlane_b32 s4, v140
	s_cmpk_lt_u32 s4, 0xc0
	s_mov_b64 s[4:5], -1
	s_cbranch_scc0 .LBB0_46
	s_sleep 4
	global_load_dword v140, v131, s[70:71] offset:2048 sc1
	s_waitcnt vmcnt(0)
	v_readfirstlane_b32 s4, v140
	s_cmpk_lt_u32 s4, 0xc0
	s_mov_b64 s[4:5], -1
	s_cbranch_scc0 .LBB0_46
	s_add_i32 s6, s6, -9
	s_cmp_eq_u32 s6, 0
	s_mov_b64 s[2:3], 0
	s_cselect_b64 s[4:5], -1, 0
	s_sleep 4
	s_branch .LBB0_46

.LBB0_167:
	global_load_dword v131, v135, s[70:71] offset:2048 sc1
	s_mov_b64 s[2:3], -1
	s_waitcnt vmcnt(0)
	v_readfirstlane_b32 s4, v131
	s_cmpk_gt_u32 s4, 0xbf
	s_mov_b64 s[4:5], -1
	s_cbranch_scc1 .LBB0_166
	s_sleep 4
	global_load_dword v131, v135, s[70:71] offset:2048 sc1
	s_waitcnt vmcnt(0)
	v_readfirstlane_b32 s4, v131
	s_cmpk_lt_u32 s4, 0xc0
	s_mov_b64 s[4:5], -1
	s_cbranch_scc0 .LBB0_166
	s_sleep 4
	global_load_dword v131, v135, s[70:71] offset:2048 sc1
	s_waitcnt vmcnt(0)
	v_readfirstlane_b32 s4, v131
	s_cmpk_lt_u32 s4, 0xc0
	s_mov_b64 s[4:5], -1
	s_cbranch_scc0 .LBB0_166
	s_sleep 4
	global_load_dword v131, v135, s[70:71] offset:2048 sc1
	s_waitcnt vmcnt(0)
	v_readfirstlane_b32 s4, v131
	s_cmpk_lt_u32 s4, 0xc0
	s_mov_b64 s[4:5], -1
	s_cbranch_scc0 .LBB0_166
	s_sleep 4
	global_load_dword v131, v135, s[70:71] offset:2048 sc1
	s_waitcnt vmcnt(0)
	v_readfirstlane_b32 s4, v131
	s_cmpk_lt_u32 s4, 0xc0
	s_mov_b64 s[4:5], -1
	s_cbranch_scc0 .LBB0_166
	s_sleep 4
	global_load_dword v131, v135, s[70:71] offset:2048 sc1
	s_waitcnt vmcnt(0)
	v_readfirstlane_b32 s4, v131
	s_cmpk_lt_u32 s4, 0xc0
	s_mov_b64 s[4:5], -1
	s_cbranch_scc0 .LBB0_166
	s_sleep 4
	global_load_dword v131, v135, s[70:71] offset:2048 sc1
	s_waitcnt vmcnt(0)
	v_readfirstlane_b32 s4, v131
	s_cmpk_lt_u32 s4, 0xc0
	s_mov_b64 s[4:5], -1
	s_cbranch_scc0 .LBB0_166
	s_sleep 4
	global_load_dword v131, v135, s[70:71] offset:2048 sc1
	s_waitcnt vmcnt(0)
	v_readfirstlane_b32 s4, v131
	s_cmpk_lt_u32 s4, 0xc0
	s_mov_b64 s[4:5], -1
	s_cbranch_scc0 .LBB0_166
	s_sleep 4
	global_load_dword v131, v135, s[70:71] offset:2048 sc1
	s_waitcnt vmcnt(0)
	v_readfirstlane_b32 s4, v131
	s_cmpk_lt_u32 s4, 0xc0
	s_mov_b64 s[4:5], -1
	s_cbranch_scc0 .LBB0_166
	s_add_i32 s6, s6, -9
	s_cmp_eq_u32 s6, 0
	s_mov_b64 s[2:3], 0
	s_cselect_b64 s[4:5], -1, 0
	s_sleep 4
	s_branch .LBB0_166

.LBB0_205:
	s_mov_b64 s[8:9], -1
	s_andn2_b64 vcc, exec, s[10:11]
	s_mov_b64 s[10:11], -1
	s_cbranch_vccnz .LBB0_202
	s_sleep 2
	global_load_dword v3, v2, s[4:5] offset:2080 sc1
	s_waitcnt vmcnt(0)
	v_readfirstlane_b32 s8, v3
	s_cmp_lt_u32 s8, 8
	s_cselect_b64 s[10:11], -1, 0
	s_cmp_gt_u32 s8, 7
	s_cbranch_scc0 .LBB0_208
	global_load_dword v3, v2, s[6:7] offset:2240 sc1
	s_waitcnt vmcnt(0)
	v_readfirstlane_b32 s8, v3
	s_cmpk_lt_u32 s8, 0x80
	s_cselect_b64 s[10:11], -1, 0

.LBB0_211:
	s_mov_b64 s[8:9], -1
	s_andn2_b64 vcc, exec, s[10:11]
	s_mov_b64 s[10:11], -1
	s_cbranch_vccnz .LBB0_202
	s_add_i32 s17, s17, -3
	s_cmp_eq_u32 s17, 0
	s_mov_b64 s[8:9], 0
	s_cselect_b64 s[10:11], -1, 0
	s_sleep 2
	s_branch .LBB0_202

.LBB0_245:
	s_mov_b64 s[44:45], -1
	s_andn2_b64 vcc, exec, s[46:47]
	s_mov_b64 s[46:47], -1
	s_cbranch_vccnz .LBB0_242
	s_sleep 2
	global_load_dword v94, v[92:93], off offset:2080 sc1
	s_waitcnt vmcnt(0)
	v_readfirstlane_b32 s44, v94
	s_cmp_lt_u32 s44, 8
	s_cselect_b64 s[46:47], -1, 0
	s_cmp_gt_u32 s44, 7
	s_cbranch_scc0 .LBB0_248
	global_load_dword v94, v141, s[40:41] offset:2240 sc1
	s_waitcnt vmcnt(0)
	v_readfirstlane_b32 s44, v94
	s_cmpk_lt_u32 s44, 0x80
	s_cselect_b64 s[46:47], -1, 0

.LBB0_251:
	s_mov_b64 s[44:45], -1
	s_andn2_b64 vcc, exec, s[46:47]
	s_mov_b64 s[46:47], -1
	s_cbranch_vccnz .LBB0_242
	s_add_i32 s2, s2, -3
	s_cmp_eq_u32 s2, 0
	s_mov_b64 s[44:45], 0
	s_cselect_b64 s[46:47], -1, 0
	s_sleep 2
	s_branch .LBB0_242

.LBB0_424:
	s_and_b32 s16, s20, 0xff
	s_mov_b64 s[14:15], -1
	s_cmp_lg_u32 s16, 0
	s_mov_b64 s[18:19], -1
	s_sleep 2
	s_cbranch_scc0 .LBB0_427
	s_and_b64 vcc, exec, s[18:19]
	s_cbranch_vccz .LBB0_423

.LBB0_441:
	s_and_b32 s16, s22, 0xff
	s_cmp_lg_u32 s16, 0
	s_mov_b64 s[18:19], -1
	s_sleep 2
	s_cbranch_scc0 .LBB0_444
	s_mov_b64 s[20:21], -1
	s_and_b64 vcc, exec, s[18:19]
	s_cbranch_vccz .LBB0_440

.LBB0_782:
	s_or_b64 exec, exec, s[6:7]
	v_cndmask_b32_e64 v2, 0, 1, s[8:9]
	v_cmp_ne_u32_e32 vcc, 0, v2
	s_cmp_eq_u64 vcc, exec
	s_mov_b64 s[6:7], -1
	s_cbranch_scc1 .LBB0_779
	s_mov_b64 s[8:9], -1
	s_sleep 4
	s_and_saveexec_b64 s[6:7], s[4:5]
	s_cbranch_execz .LBB0_785
	global_load_dword v2, v[36:37], off sc1
	s_waitcnt vmcnt(0)
	v_cmp_ne_u32_e32 vcc, 0, v2
	s_orn2_b64 s[8:9], vcc, exec

.LBB0_788:
	s_or_b64 exec, exec, s[6:7]
	v_cndmask_b32_e64 v2, 0, 1, s[8:9]
	v_cmp_ne_u32_e32 vcc, 0, v2
	s_cmp_eq_u64 vcc, exec
	s_mov_b64 s[6:7], -1
	s_cbranch_scc1 .LBB0_779
	s_add_i32 s1, s1, -3
	s_cmp_eq_u32 s1, 0
	s_mov_b64 s[2:3], 0
	s_cselect_b64 s[6:7], -1, 0
	s_sleep 4
	s_branch .LBB0_779

.LBB0_832:
	global_load_dword v18, v[36:37], off sc1
	s_mov_b64 s[38:39], -1
	s_mov_b64 s[40:41], -1
	s_waitcnt vmcnt(0)
	v_cmp_ne_u32_e32 vcc, 0, v18
	s_cmp_eq_u64 vcc, exec
	s_cbranch_scc1 .LBB0_831
	s_sleep 4
	global_load_dword v18, v[36:37], off sc1
	s_waitcnt vmcnt(0)
	v_cmp_ne_u32_e32 vcc, 0, v18
	s_cmp_lg_u64 vcc, exec
	s_cbranch_scc0 .LBB0_831
	s_sleep 4
	global_load_dword v18, v[36:37], off sc1
	s_waitcnt vmcnt(0)
	v_cmp_ne_u32_e32 vcc, 0, v18
	s_cmp_lg_u64 vcc, exec
	s_cbranch_scc0 .LBB0_831
	s_add_i32 s62, s62, -3
	s_cmp_eq_u32 s62, 0
	s_mov_b64 s[38:39], 0
	s_cselect_b64 s[40:41], -1, 0
	s_sleep 4
	s_branch .LBB0_831

.LBB0_984:
	s_and_b32 s18, s22, 0xff
	s_mov_b64 s[16:17], -1
	s_cmp_lg_u32 s18, 0
	s_mov_b64 s[20:21], -1
	s_sleep 2
	s_cbranch_scc0 .LBB0_987
	s_and_b64 vcc, exec, s[20:21]
	s_cbranch_vccz .LBB0_983

.LBB0_1001:
	s_and_b32 s18, s24, 0xff
	s_cmp_lg_u32 s18, 0
	s_mov_b64 s[20:21], -1
	s_sleep 2
	s_cbranch_scc0 .LBB0_1004
	s_mov_b64 s[22:23], -1
	s_and_b64 vcc, exec, s[20:21]
	s_cbranch_vccz .LBB0_1000
